# FFN1 swiglu epilogue: the two 8-byte stores per row merged into one 16-byte store via v_permlane16_swap (12 dwordx2 -> 6 dwordx4 per tile)
# speedup vs baseline: 1.0449x; 1.0001x over previous
; template <int EPI>
; __device__ __forceinline__ void gemm_tile3(const Params& p, int l, const u16* __restrict__ A, int lda, const u16* __restrict__ Bt, int K, int m0, int n0, unsigned char* smem) {
;     ...
;             DSR128(bv[0], lb, 0); DSR128(bv[1], lb, 1024); DSR128(bv[2], lb, 2048); DSR128(bv[3], lb, 3072);
;             DSR128(af[0], la, 0); DSR128(af[1], la, 1024); DSR128(af[2], la, 2048); DSR128(af[3], la, 3072); DSR128(af[4], la, 4096); DSR128(af[5], la, 5120);
;         }
;         __builtin_amdgcn_sched_barrier(0);
;         asm volatile("s_waitcnt lgkmcnt(5)" : "+v"(bv[0]), "+v"(bv[1]), "+v"(bv[2]), "+v"(bv[3]), "+v"(af[0]));
;         __builtin_amdgcn_sched_barrier(0);
; #pragma unroll
;         for (int j = 0; j < 4; ++j) acc[0][j] = __builtin_amdgcn_mfma_f32_16x16x32_bf16(bv[j], af[0], acc[0][j], 0, 0, 0);
;         __builtin_amdgcn_sched_barrier(0);
;         asm volatile("s_waitcnt lgkmcnt(4)" : "+v"(af[1]));
;         __builtin_amdgcn_sched_barrier(0);
; #pragma unroll
;         for (int j = 0; j < 4; ++j) acc[1][j] = __builtin_amdgcn_mfma_f32_16x16x32_bf16(bv[j], af[1], acc[1][j], 0, 0, 0);
;         __builtin_amdgcn_sched_barrier(0);
;         asm volatile("s_waitcnt lgkmcnt(3)" : "+v"(af[2]));
;         __builtin_amdgcn_sched_barrier(0);
; #pragma unroll
;         for (int j = 0; j < 4; ++j) acc[2][j] = __builtin_amdgcn_mfma_f32_16x16x32_bf16(bv[j], af[2], acc[2][j], 0, 0, 0);
;         __builtin_amdgcn_sched_barrier(0);
;         asm volatile("s_waitcnt lgkmcnt(2)" : "+v"(af[3]));
;         __builtin_amdgcn_sched_barrier(0);
; #pragma unroll
;         for (int j = 0; j < 4; ++j) acc[3][j] = __builtin_amdgcn_mfma_f32_16x16x32_bf16(bv[j], af[3], acc[3][j], 0, 0, 0);
;         __builtin_amdgcn_sched_barrier(0);
;         asm volatile("s_waitcnt lgkmcnt(1)" : "+v"(af[4]));
;         __builtin_amdgcn_sched_barrier(0);
; #pragma unroll
;         for (int j = 0; j < 4; ++j) acc[4][j] = __builtin_amdgcn_mfma_f32_16x16x32_bf16(bv[j], af[4], acc[4][j], 0, 0, 0);
;         __builtin_amdgcn_sched_barrier(0);
;         asm volatile("s_waitcnt lgkmcnt(0)" : "+v"(af[5]));
;         __builtin_amdgcn_sched_barrier(0);
; #pragma unroll
;         for (int j = 0; j < 4; ++j) acc[5][j] = __builtin_amdgcn_mfma_f32_16x16x32_bf16(bv[j], af[5], acc[5][j], 0, 0, 0);
;     ...
;         u16* actb = (u16*)(p.ws + OFF_ACT);
.LBB0_892:
	s_waitcnt vmcnt(0)
	s_barrier
	v_add_u32_e32 v0, 0xf000, v108
	v_add_u32_e32 v98, 0x12000, v109
	ds_read_b128 v[108:111], v98 offset:0
	ds_read_b128 v[112:115], v98 offset:1024
	ds_read_b128 v[116:119], v98 offset:2048
	ds_read_b128 v[120:123], v98 offset:3072
	ds_read_b128 v[124:127], v0 offset:0
	ds_read_b128 v[128:131], v0 offset:1024
	ds_read_b128 v[132:135], v0 offset:2048
	ds_read_b128 v[136:139], v0 offset:3072
	ds_read_b128 v[140:143], v0 offset:4096
	ds_read_b128 v[144:147], v0 offset:5120
	s_nop 0
	s_waitcnt lgkmcnt(5)
	s_nop 0
	v_mfma_f32_16x16x32_bf16 v[94:97], v[108:111], v[124:127], v[94:97]
	v_mfma_f32_16x16x32_bf16 v[90:93], v[112:115], v[124:127], v[90:93]
	v_mfma_f32_16x16x32_bf16 v[86:89], v[116:119], v[124:127], v[86:89]
	v_mfma_f32_16x16x32_bf16 v[82:85], v[120:123], v[124:127], v[82:85]
	s_waitcnt lgkmcnt(4)
	s_nop 0
	v_mfma_f32_16x16x32_bf16 v[78:81], v[108:111], v[128:131], v[78:81]
	v_mfma_f32_16x16x32_bf16 v[74:77], v[112:115], v[128:131], v[74:77]
	v_mfma_f32_16x16x32_bf16 v[66:69], v[116:119], v[128:131], v[66:69]
	v_mfma_f32_16x16x32_bf16 v[70:73], v[120:123], v[128:131], v[70:73]
	s_waitcnt lgkmcnt(3)
	s_nop 0
	v_mfma_f32_16x16x32_bf16 v[62:65], v[108:111], v[132:135], v[62:65]
	v_mfma_f32_16x16x32_bf16 v[58:61], v[112:115], v[132:135], v[58:61]
	v_mfma_f32_16x16x32_bf16 v[50:53], v[116:119], v[132:135], v[50:53]
	v_mfma_f32_16x16x32_bf16 v[54:57], v[120:123], v[132:135], v[54:57]
	s_waitcnt lgkmcnt(2)
	s_nop 0
	v_mfma_f32_16x16x32_bf16 v[46:49], v[108:111], v[136:139], v[46:49]
	v_mfma_f32_16x16x32_bf16 v[42:45], v[112:115], v[136:139], v[42:45]
	v_mfma_f32_16x16x32_bf16 v[34:37], v[116:119], v[136:139], v[34:37]
	v_mfma_f32_16x16x32_bf16 v[38:41], v[120:123], v[136:139], v[38:41]
	s_waitcnt lgkmcnt(1)
	s_nop 0
	v_mfma_f32_16x16x32_bf16 v[30:33], v[108:111], v[140:143], v[30:33]
	v_mfma_f32_16x16x32_bf16 v[26:29], v[112:115], v[140:143], v[26:29]
	v_mfma_f32_16x16x32_bf16 v[18:21], v[116:119], v[140:143], v[18:21]
	v_mfma_f32_16x16x32_bf16 v[22:25], v[120:123], v[140:143], v[22:25]
	s_waitcnt lgkmcnt(0)
	v_or_b32_e32 v0, s23, v103
	s_movk_i32 s0, 0x60
	v_mad_u64_u32 v[100:101], s[0:1], v99, s0, v[0:1]
	v_mov_b32_e32 v103, v1
	v_mul_f32_e32 v0, 0xbfb8aa3b, v94
	v_lshl_add_u64 v[98:99], s[26:27], 0, v[102:103]
	v_exp_f32_e32 v102, v0
	v_mul_f32_e32 v0, 0xbfb8aa3b, v95
	v_exp_f32_e32 v103, v0
	v_mfma_f32_16x16x32_bf16 v[14:17], v[108:111], v[144:147], v[14:17]
	v_ashrrev_i32_e32 v101, 4, v100
	s_movk_i32 s16, 0x58
	v_pk_add_f32 v[102:103], v[102:103], 1.0 op_sel_hi:[1,0]
	s_waitcnt vmcnt(0) lgkmcnt(0)
	v_div_scale_f32 v0, s[0:1], v103, v103, v95
	v_rcp_f32_e32 v104, v0
	s_barrier
	v_mfma_f32_16x16x32_bf16 v[10:13], v[112:115], v[144:147], v[10:13]
	v_fma_f32 v105, -v0, v104, 1.0
	v_fmac_f32_e32 v104, v105, v104
	v_div_scale_f32 v105, vcc, v95, v103, v95
	v_mul_f32_e32 v108, v105, v104
	v_fma_f32 v109, -v0, v108, v105
	v_fmac_f32_e32 v108, v109, v104
	v_fma_f32 v0, -v0, v108, v105
	v_div_fmas_f32 v0, v0, v104, v108
	v_div_fixup_f32 v95, v0, v103, v95
	v_div_scale_f32 v0, s[0:1], v102, v102, v94
	v_rcp_f32_e32 v103, v0
	v_mfma_f32_16x16x32_bf16 v[6:9], v[116:119], v[144:147], v[6:9]
	s_add_i32 s41, s41, 1
	v_fma_f32 v104, -v0, v103, 1.0
	v_fmac_f32_e32 v103, v104, v103
	v_div_scale_f32 v104, vcc, v94, v102, v94
	v_mul_f32_e32 v105, v104, v103
	v_fma_f32 v108, -v0, v105, v104
	v_fmac_f32_e32 v105, v108, v103
	v_fma_f32 v0, -v0, v105, v104
	v_div_fmas_f32 v0, v0, v103, v105
	v_div_fixup_f32 v94, v0, v102, v94
	v_mul_f32_e32 v0, 0xbfb8aa3b, v96
	v_pk_mul_f32 v[90:91], v[90:91], v[94:95]
	v_exp_f32_e32 v94, v0
	v_mul_f32_e32 v0, 0xbfb8aa3b, v97
	v_exp_f32_e32 v95, v0
	v_mfma_f32_16x16x32_bf16 v[2:5], v[120:123], v[144:147], v[2:5]
	v_add_f32_e64 v94, v94, 1.0
	v_add_f32_e64 v95, v95, 1.0
	v_div_scale_f32 v0, s[0:1], v95, v95, v97
	v_rcp_f32_e32 v102, v0
	s_nop 0
	v_fma_f32 v103, -v0, v102, 1.0
	v_fmac_f32_e32 v102, v103, v102
	v_div_scale_f32 v103, vcc, v97, v95, v97
	v_mul_f32_e32 v104, v103, v102
	v_fma_f32 v105, -v0, v104, v103
	v_fmac_f32_e32 v104, v105, v102
	v_fma_f32 v0, -v0, v104, v103
	v_div_fmas_f32 v0, v0, v102, v104
	v_div_fixup_f32 v95, v0, v95, v97
	v_div_scale_f32 v0, s[0:1], v94, v94, v96
	v_rcp_f32_e32 v97, v0
	s_ashr_i32 s0, s49, 6
	v_fma_f32 v102, -v0, v97, 1.0
	v_fmac_f32_e32 v97, v102, v97
	v_div_scale_f32 v102, vcc, v96, v94, v96
	v_mul_f32_e32 v103, v102, v97
	v_fma_f32 v104, -v0, v103, v102
	v_fmac_f32_e32 v103, v104, v97
	v_fma_f32 v0, -v0, v103, v102
	v_div_fmas_f32 v0, v0, v97, v103
	v_div_fixup_f32 v94, v0, v94, v96
	v_pk_mul_f32 v[92:93], v[92:93], v[94:95]
	v_cvt_pk_bf16_f32 v94, v90, v91
	v_or_b32_e32 v90, s0, v107
	v_ashrrev_i32_e32 v91, 31, v90
	v_cvt_pk_bf16_f32 v95, v92, v93
	v_mad_i64_i32 v[92:93], s[0:1], v101, s16, v[90:91]
	v_lshlrev_b64 v[92:93], 10, v[92:93]
	v_lshrrev_b32_e32 v0, 1, v106
	v_lshl_add_u64 v[92:93], v[98:99], 0, v[92:93]
	v_and_b32_e32 v0, 24, v0
	v_and_b32_e32 v252, 16, v106
	v_add_u32_e32 v0, v0, v252
	v_lshrrev_b32_e32 v252, 1, v252
	v_add_u32_e32 v0, v0, v252
	v_lshl_add_u64 v[92:93], v[92:93], 0, v[0:1]
	v_mov_b32_e32 v252, v94
	v_mov_b32_e32 v253, v95
	v_mul_f32_e32 v94, 0xbfb8aa3b, v86
	v_mul_f32_e32 v95, 0xbfb8aa3b, v87
	v_exp_f32_e32 v94, v94
	v_exp_f32_e32 v95, v95
	s_nop 0
	v_pk_add_f32 v[94:95], v[94:95], 1.0 op_sel_hi:[1,0]
	s_nop 0
	v_div_scale_f32 v96, s[0:1], v95, v95, v87
	v_rcp_f32_e32 v97, v96
	s_nop 0
	v_fma_f32 v102, -v96, v97, 1.0
	v_fmac_f32_e32 v97, v102, v97
	v_div_scale_f32 v102, vcc, v87, v95, v87
	v_mul_f32_e32 v103, v102, v97
	v_fma_f32 v104, -v96, v103, v102
	v_fmac_f32_e32 v103, v104, v97
	v_fma_f32 v96, -v96, v103, v102
; __device__ __forceinline__ size_t tiled_off(int row, int k, int K) { return ((size_t)(row >> 4) * (K >> 5) + (k >> 5)) * 512 + (row & 15) * 32 + (k & 31); }
; template <int EPI>
; __device__ __forceinline__ void gemm_tile3(const Params& p, int l, const u16* __restrict__ A, int lda, const u16* __restrict__ Bt, int K, int m0, int n0, unsigned char* smem) {
;     ...
;         u16* actb = (u16*)(p.ws + OFF_ACT);
;         const int colb = (n0 >> 1) + wc * 32 + fq * 4;
; #pragma unroll
;         for (int i = 0; i < 6; ++i)
; #pragma unroll
;             for (int jp = 0; jp < 2; ++jp) {
;                 float o[4];
; #pragma unroll
;                 for (int r = 0; r < 4; ++r) { const float g = acc[i][2 * jp][r], u = acc[i][2 * jp + 1][r]; o[r] = g / (1.f + __expf(-g)) * u; }
;                 u32x2 w; w[0] = pk2(o[0], o[1]); w[1] = pk2(o[2], o[3]);
;                 *(u32x2*)(actb + tiled_off(rowb + i * 16, colb + jp * 16, FFH)) = w;
;             }
	v_div_fmas_f32 v96, v96, v97, v103
	v_div_fixup_f32 v87, v96, v95, v87
	v_div_scale_f32 v95, s[0:1], v94, v94, v86
	v_rcp_f32_e32 v96, v95
	s_nop 0
	v_fma_f32 v97, -v95, v96, 1.0
	v_fmac_f32_e32 v96, v97, v96
	v_div_scale_f32 v97, vcc, v86, v94, v86
	v_mul_f32_e32 v102, v97, v96
	v_fma_f32 v103, -v95, v102, v97
	v_fmac_f32_e32 v102, v103, v96
	v_fma_f32 v95, -v95, v102, v97
	v_div_fmas_f32 v95, v95, v96, v102
	v_div_fixup_f32 v86, v95, v94, v86
	v_pk_mul_f32 v[82:83], v[82:83], v[86:87]
	v_mul_f32_e32 v86, 0xbfb8aa3b, v88
	v_mul_f32_e32 v87, 0xbfb8aa3b, v89
	v_exp_f32_e32 v86, v86
	v_exp_f32_e32 v87, v87
	v_cvt_pk_bf16_f32 v82, v82, v83
	v_pk_add_f32 v[86:87], v[86:87], 1.0 op_sel_hi:[1,0]
	s_nop 0
	v_div_scale_f32 v94, s[0:1], v87, v87, v89
	v_rcp_f32_e32 v95, v94
	s_nop 0
	v_fma_f32 v96, -v94, v95, 1.0
	v_fmac_f32_e32 v95, v96, v95
	v_div_scale_f32 v96, vcc, v89, v87, v89
	v_mul_f32_e32 v97, v96, v95
	v_fma_f32 v102, -v94, v97, v96
	v_fmac_f32_e32 v97, v102, v95
	v_fma_f32 v94, -v94, v97, v96
	v_div_fmas_f32 v94, v94, v95, v97
	v_div_fixup_f32 v87, v94, v87, v89
	v_div_scale_f32 v89, s[0:1], v86, v86, v88
	v_rcp_f32_e32 v94, v89
	s_nop 0
	v_fma_f32 v95, -v89, v94, 1.0
	v_fmac_f32_e32 v94, v95, v94
	v_div_scale_f32 v95, vcc, v88, v86, v88
	v_mul_f32_e32 v96, v95, v94
	v_fma_f32 v97, -v89, v96, v95
	v_fmac_f32_e32 v96, v97, v94
	v_fma_f32 v89, -v89, v96, v95
	v_div_fmas_f32 v89, v89, v94, v96
	v_div_fixup_f32 v86, v89, v86, v88
	v_pk_mul_f32 v[84:85], v[84:85], v[86:87]
	s_nop 0
	v_cvt_pk_bf16_f32 v83, v84, v85
	v_mov_b32_e32 v254, v82
	v_mov_b32_e32 v255, v83
	s_nop 1
	v_permlane16_swap_b32_e32 v252, v254
	v_permlane16_swap_b32_e32 v253, v255
	global_store_dwordx4 v[92:93], v[252:255], off
	v_mul_f32_e32 v82, 0xbfb8aa3b, v78
	v_mul_f32_e32 v83, 0xbfb8aa3b, v79
	v_exp_f32_e32 v82, v82
	v_exp_f32_e32 v83, v83
	v_or_b32_e32 v84, 1, v101
	v_pk_add_f32 v[82:83], v[82:83], 1.0 op_sel_hi:[1,0]
	s_nop 0
	v_div_scale_f32 v85, s[0:1], v83, v83, v79
	v_rcp_f32_e32 v86, v85
	s_nop 0
	v_fma_f32 v87, -v85, v86, 1.0
	v_fmac_f32_e32 v86, v87, v86
	v_div_scale_f32 v87, vcc, v79, v83, v79
	v_mul_f32_e32 v88, v87, v86
	v_fma_f32 v89, -v85, v88, v87
	v_fmac_f32_e32 v88, v89, v86
	v_fma_f32 v85, -v85, v88, v87
	v_div_fmas_f32 v85, v85, v86, v88
	v_div_fixup_f32 v79, v85, v83, v79
	v_div_scale_f32 v83, s[0:1], v82, v82, v78
	v_rcp_f32_e32 v85, v83
	s_nop 0
	v_fma_f32 v86, -v83, v85, 1.0
	v_fmac_f32_e32 v85, v86, v85
	v_div_scale_f32 v86, vcc, v78, v82, v78
	v_mul_f32_e32 v87, v86, v85
	v_fma_f32 v88, -v83, v87, v86
	v_fmac_f32_e32 v87, v88, v85
	v_fma_f32 v83, -v83, v87, v86
	v_div_fmas_f32 v83, v83, v85, v87
	v_div_fixup_f32 v78, v83, v82, v78
	v_pk_mul_f32 v[74:75], v[74:75], v[78:79]
	v_mul_f32_e32 v78, 0xbfb8aa3b, v80
	v_mul_f32_e32 v79, 0xbfb8aa3b, v81
	v_exp_f32_e32 v78, v78
	v_exp_f32_e32 v79, v79
	v_cvt_pk_bf16_f32 v74, v74, v75
	v_pk_add_f32 v[78:79], v[78:79], 1.0 op_sel_hi:[1,0]
	s_nop 0
	v_div_scale_f32 v82, s[0:1], v79, v79, v81
	v_rcp_f32_e32 v83, v82
	s_nop 0
	v_fma_f32 v85, -v82, v83, 1.0
	v_fmac_f32_e32 v83, v85, v83
	v_div_scale_f32 v85, vcc, v81, v79, v81
	v_mul_f32_e32 v86, v85, v83
	v_fma_f32 v87, -v82, v86, v85
	v_fmac_f32_e32 v86, v87, v83
	v_fma_f32 v82, -v82, v86, v85
	v_div_fmas_f32 v82, v82, v83, v86
	v_div_fixup_f32 v79, v82, v79, v81
	v_div_scale_f32 v81, s[0:1], v78, v78, v80
	v_rcp_f32_e32 v82, v81
	s_nop 0
	v_fma_f32 v83, -v81, v82, 1.0
	v_fmac_f32_e32 v82, v83, v82
	v_div_scale_f32 v83, vcc, v80, v78, v80
	v_mul_f32_e32 v85, v83, v82
	v_fma_f32 v86, -v81, v85, v83
	v_fmac_f32_e32 v85, v86, v82
	v_fma_f32 v81, -v81, v85, v83
	v_div_fmas_f32 v81, v81, v82, v85
	v_div_fixup_f32 v78, v81, v78, v80
	v_pk_mul_f32 v[76:77], v[76:77], v[78:79]
	s_nop 0
	v_cvt_pk_bf16_f32 v75, v76, v77
	v_mad_i64_i32 v[76:77], s[0:1], v84, s16, v[90:91]
	v_lshlrev_b64 v[76:77], 10, v[76:77]
	v_lshl_add_u64 v[76:77], v[98:99], 0, v[76:77]
	v_lshl_add_u64 v[76:77], v[76:77], 0, v[0:1]
	v_mov_b32_e32 v252, v74
	v_mov_b32_e32 v253, v75
	v_mul_f32_e32 v74, 0xbfb8aa3b, v66
	v_mul_f32_e32 v75, 0xbfb8aa3b, v67
	v_exp_f32_e32 v74, v74
	v_exp_f32_e32 v75, v75
	s_nop 0
	v_pk_add_f32 v[74:75], v[74:75], 1.0 op_sel_hi:[1,0]
	s_nop 0
	v_div_scale_f32 v78, s[0:1], v75, v75, v67
	v_rcp_f32_e32 v79, v78
	s_nop 0
	v_fma_f32 v80, -v78, v79, 1.0
	v_fmac_f32_e32 v79, v80, v79
	v_div_scale_f32 v80, vcc, v67, v75, v67
	v_mul_f32_e32 v81, v80, v79
	v_fma_f32 v82, -v78, v81, v80
	v_fmac_f32_e32 v81, v82, v79
	v_fma_f32 v78, -v78, v81, v80
	v_div_fmas_f32 v78, v78, v79, v81
	v_div_fixup_f32 v67, v78, v75, v67
	v_div_scale_f32 v75, s[0:1], v74, v74, v66
	v_rcp_f32_e32 v78, v75
	s_nop 0
	v_fma_f32 v79, -v75, v78, 1.0
	v_fmac_f32_e32 v78, v79, v78
	v_div_scale_f32 v79, vcc, v66, v74, v66
	v_mul_f32_e32 v80, v79, v78
	v_fma_f32 v81, -v75, v80, v79
	v_fmac_f32_e32 v80, v81, v78
	v_fma_f32 v75, -v75, v80, v79
	v_div_fmas_f32 v75, v75, v78, v80
	v_div_fixup_f32 v66, v75, v74, v66
	v_pk_mul_f32 v[66:67], v[70:71], v[66:67]
	v_mul_f32_e32 v70, 0xbfb8aa3b, v68
	v_mul_f32_e32 v71, 0xbfb8aa3b, v69
	v_exp_f32_e32 v70, v70
	v_exp_f32_e32 v71, v71
	v_cvt_pk_bf16_f32 v66, v66, v67
	v_pk_add_f32 v[70:71], v[70:71], 1.0 op_sel_hi:[1,0]
	s_nop 0
	v_div_scale_f32 v74, s[0:1], v71, v71, v69
	v_rcp_f32_e32 v75, v74
	s_nop 0
	v_fma_f32 v78, -v74, v75, 1.0
	v_fmac_f32_e32 v75, v78, v75
	v_div_scale_f32 v78, vcc, v69, v71, v69
	v_mul_f32_e32 v79, v78, v75
	v_fma_f32 v80, -v74, v79, v78
	v_fmac_f32_e32 v79, v80, v75
	v_fma_f32 v74, -v74, v79, v78
	v_div_fmas_f32 v74, v74, v75, v79
	v_div_fixup_f32 v69, v74, v71, v69
	v_div_scale_f32 v71, s[0:1], v70, v70, v68
	v_rcp_f32_e32 v74, v71
	s_nop 0
; __device__ __forceinline__ size_t tiled_off(int row, int k, int K) { return ((size_t)(row >> 4) * (K >> 5) + (k >> 5)) * 512 + (row & 15) * 32 + (k & 31); }
; template <int EPI>
; __device__ __forceinline__ void gemm_tile3(const Params& p, int l, const u16* __restrict__ A, int lda, const u16* __restrict__ Bt, int K, int m0, int n0, unsigned char* smem) {
;     ...
;         u16* actb = (u16*)(p.ws + OFF_ACT);
;         const int colb = (n0 >> 1) + wc * 32 + fq * 4;
; #pragma unroll
;         for (int i = 0; i < 6; ++i)
; #pragma unroll
;             for (int jp = 0; jp < 2; ++jp) {
;                 float o[4];
; #pragma unroll
;                 for (int r = 0; r < 4; ++r) { const float g = acc[i][2 * jp][r], u = acc[i][2 * jp + 1][r]; o[r] = g / (1.f + __expf(-g)) * u; }
;                 u32x2 w; w[0] = pk2(o[0], o[1]); w[1] = pk2(o[2], o[3]);
;                 *(u32x2*)(actb + tiled_off(rowb + i * 16, colb + jp * 16, FFH)) = w;
;             }
	v_fma_f32 v75, -v71, v74, 1.0
	v_fmac_f32_e32 v74, v75, v74
	v_div_scale_f32 v75, vcc, v68, v70, v68
	v_mul_f32_e32 v78, v75, v74
	v_fma_f32 v79, -v71, v78, v75
	v_fmac_f32_e32 v78, v79, v74
	v_fma_f32 v71, -v71, v78, v75
	v_div_fmas_f32 v71, v71, v74, v78
	v_div_fixup_f32 v68, v71, v70, v68
	v_pk_mul_f32 v[68:69], v[72:73], v[68:69]
	s_nop 0
	v_cvt_pk_bf16_f32 v67, v68, v69
	v_mov_b32_e32 v254, v66
	v_mov_b32_e32 v255, v67
	s_nop 1
	v_permlane16_swap_b32_e32 v252, v254
	v_permlane16_swap_b32_e32 v253, v255
	global_store_dwordx4 v[76:77], v[252:255], off
	v_add_u32_e32 v66, 32, v100
	v_ashrrev_i32_e32 v68, 4, v66
	v_mul_f32_e32 v66, 0xbfb8aa3b, v62
	v_mul_f32_e32 v67, 0xbfb8aa3b, v63
	v_exp_f32_e32 v66, v66
	v_exp_f32_e32 v67, v67
	s_nop 0
	v_pk_add_f32 v[66:67], v[66:67], 1.0 op_sel_hi:[1,0]
	s_nop 0
	v_div_scale_f32 v69, s[0:1], v67, v67, v63
	v_rcp_f32_e32 v70, v69
	s_nop 0
	v_fma_f32 v71, -v69, v70, 1.0
	v_fmac_f32_e32 v70, v71, v70
	v_div_scale_f32 v71, vcc, v63, v67, v63
	v_mul_f32_e32 v72, v71, v70
	v_fma_f32 v73, -v69, v72, v71
	v_fmac_f32_e32 v72, v73, v70
	v_fma_f32 v69, -v69, v72, v71
	v_div_fmas_f32 v69, v69, v70, v72
	v_div_fixup_f32 v63, v69, v67, v63
	v_div_scale_f32 v67, s[0:1], v66, v66, v62
	v_rcp_f32_e32 v69, v67
	s_nop 0
	v_fma_f32 v70, -v67, v69, 1.0
	v_fmac_f32_e32 v69, v70, v69
	v_div_scale_f32 v70, vcc, v62, v66, v62
	v_mul_f32_e32 v71, v70, v69
	v_fma_f32 v72, -v67, v71, v70
	v_fmac_f32_e32 v71, v72, v69
	v_fma_f32 v67, -v67, v71, v70
	v_div_fmas_f32 v67, v67, v69, v71
	v_div_fixup_f32 v62, v67, v66, v62
	v_pk_mul_f32 v[58:59], v[58:59], v[62:63]
	v_mul_f32_e32 v62, 0xbfb8aa3b, v64
	v_mul_f32_e32 v63, 0xbfb8aa3b, v65
	v_exp_f32_e32 v62, v62
	v_exp_f32_e32 v63, v63
	v_cvt_pk_bf16_f32 v58, v58, v59
	v_pk_add_f32 v[62:63], v[62:63], 1.0 op_sel_hi:[1,0]
	s_nop 0
	v_div_scale_f32 v66, s[0:1], v63, v63, v65
	v_rcp_f32_e32 v67, v66
	s_nop 0
	v_fma_f32 v69, -v66, v67, 1.0
	v_fmac_f32_e32 v67, v69, v67
	v_div_scale_f32 v69, vcc, v65, v63, v65
	v_mul_f32_e32 v70, v69, v67
	v_fma_f32 v71, -v66, v70, v69
	v_fmac_f32_e32 v70, v71, v67
	v_fma_f32 v66, -v66, v70, v69
	v_div_fmas_f32 v66, v66, v67, v70
	v_div_fixup_f32 v63, v66, v63, v65
	v_div_scale_f32 v65, s[0:1], v62, v62, v64
	v_rcp_f32_e32 v66, v65
	s_nop 0
	v_fma_f32 v67, -v65, v66, 1.0
	v_fmac_f32_e32 v66, v67, v66
	v_div_scale_f32 v67, vcc, v64, v62, v64
	v_mul_f32_e32 v69, v67, v66
	v_fma_f32 v70, -v65, v69, v67
	v_fmac_f32_e32 v69, v70, v66
	v_fma_f32 v65, -v65, v69, v67
	v_div_fmas_f32 v65, v65, v66, v69
	v_div_fixup_f32 v62, v65, v62, v64
	v_pk_mul_f32 v[60:61], v[60:61], v[62:63]
	s_nop 0
	v_cvt_pk_bf16_f32 v59, v60, v61
	v_mad_i64_i32 v[60:61], s[0:1], v68, s16, v[90:91]
	v_lshlrev_b64 v[60:61], 10, v[60:61]
	v_lshl_add_u64 v[60:61], v[98:99], 0, v[60:61]
	v_lshl_add_u64 v[60:61], v[60:61], 0, v[0:1]
	v_mov_b32_e32 v252, v58
	v_mov_b32_e32 v253, v59
	v_mul_f32_e32 v58, 0xbfb8aa3b, v50
	v_mul_f32_e32 v59, 0xbfb8aa3b, v51
	v_exp_f32_e32 v58, v58
	v_exp_f32_e32 v59, v59
	s_nop 0
	v_pk_add_f32 v[58:59], v[58:59], 1.0 op_sel_hi:[1,0]
	s_nop 0
	v_div_scale_f32 v62, s[0:1], v59, v59, v51
	v_rcp_f32_e32 v63, v62
	s_nop 0
	v_fma_f32 v64, -v62, v63, 1.0
	v_fmac_f32_e32 v63, v64, v63
	v_div_scale_f32 v64, vcc, v51, v59, v51
	v_mul_f32_e32 v65, v64, v63
	v_fma_f32 v66, -v62, v65, v64
	v_fmac_f32_e32 v65, v66, v63
	v_fma_f32 v62, -v62, v65, v64
	v_div_fmas_f32 v62, v62, v63, v65
	v_div_fixup_f32 v51, v62, v59, v51
	v_div_scale_f32 v59, s[0:1], v58, v58, v50
	v_rcp_f32_e32 v62, v59
	s_nop 0
	v_fma_f32 v63, -v59, v62, 1.0
	v_fmac_f32_e32 v62, v63, v62
	v_div_scale_f32 v63, vcc, v50, v58, v50
	v_mul_f32_e32 v64, v63, v62
	v_fma_f32 v65, -v59, v64, v63
	v_fmac_f32_e32 v64, v65, v62
	v_fma_f32 v59, -v59, v64, v63
	v_div_fmas_f32 v59, v59, v62, v64
	v_div_fixup_f32 v50, v59, v58, v50
	v_pk_mul_f32 v[50:51], v[54:55], v[50:51]
	v_mul_f32_e32 v54, 0xbfb8aa3b, v52
	v_mul_f32_e32 v55, 0xbfb8aa3b, v53
	v_exp_f32_e32 v54, v54
	v_exp_f32_e32 v55, v55
	v_cvt_pk_bf16_f32 v50, v50, v51
	v_pk_add_f32 v[54:55], v[54:55], 1.0 op_sel_hi:[1,0]
	s_nop 0
	v_div_scale_f32 v58, s[0:1], v55, v55, v53
	v_rcp_f32_e32 v59, v58
	s_nop 0
	v_fma_f32 v62, -v58, v59, 1.0
	v_fmac_f32_e32 v59, v62, v59
	v_div_scale_f32 v62, vcc, v53, v55, v53
	v_mul_f32_e32 v63, v62, v59
	v_fma_f32 v64, -v58, v63, v62
	v_fmac_f32_e32 v63, v64, v59
	v_fma_f32 v58, -v58, v63, v62
	v_div_fmas_f32 v58, v58, v59, v63
	v_div_fixup_f32 v53, v58, v55, v53
	v_div_scale_f32 v55, s[0:1], v54, v54, v52
	v_rcp_f32_e32 v58, v55
	s_nop 0
	v_fma_f32 v59, -v55, v58, 1.0
	v_fmac_f32_e32 v58, v59, v58
	v_div_scale_f32 v59, vcc, v52, v54, v52
	v_mul_f32_e32 v62, v59, v58
	v_fma_f32 v63, -v55, v62, v59
	v_fmac_f32_e32 v62, v63, v58
	v_fma_f32 v55, -v55, v62, v59
	v_div_fmas_f32 v55, v55, v58, v62
	v_div_fixup_f32 v52, v55, v54, v52
	v_pk_mul_f32 v[52:53], v[56:57], v[52:53]
	s_nop 0
	v_cvt_pk_bf16_f32 v51, v52, v53
	v_mov_b32_e32 v254, v50
	v_mov_b32_e32 v255, v51
	s_nop 1
	v_permlane16_swap_b32_e32 v252, v254
	v_permlane16_swap_b32_e32 v253, v255
	global_store_dwordx4 v[60:61], v[252:255], off
	v_add_u32_e32 v50, 48, v100
	v_ashrrev_i32_e32 v52, 4, v50
	v_mul_f32_e32 v50, 0xbfb8aa3b, v46
	v_mul_f32_e32 v51, 0xbfb8aa3b, v47
	v_exp_f32_e32 v50, v50
	v_exp_f32_e32 v51, v51
	s_nop 0
	v_pk_add_f32 v[50:51], v[50:51], 1.0 op_sel_hi:[1,0]
	s_nop 0
	v_div_scale_f32 v53, s[0:1], v51, v51, v47
	v_rcp_f32_e32 v54, v53
	s_nop 0
	v_fma_f32 v55, -v53, v54, 1.0
	v_fmac_f32_e32 v54, v55, v54
	v_div_scale_f32 v55, vcc, v47, v51, v47
	v_mul_f32_e32 v56, v55, v54
	v_fma_f32 v57, -v53, v56, v55
	v_fmac_f32_e32 v56, v57, v54
	v_fma_f32 v53, -v53, v56, v55
; __device__ __forceinline__ size_t tiled_off(int row, int k, int K) { return ((size_t)(row >> 4) * (K >> 5) + (k >> 5)) * 512 + (row & 15) * 32 + (k & 31); }
; template <int EPI>
; __device__ __forceinline__ void gemm_tile3(const Params& p, int l, const u16* __restrict__ A, int lda, const u16* __restrict__ Bt, int K, int m0, int n0, unsigned char* smem) {
;     ...
;         u16* actb = (u16*)(p.ws + OFF_ACT);
;         const int colb = (n0 >> 1) + wc * 32 + fq * 4;
; #pragma unroll
;         for (int i = 0; i < 6; ++i)
; #pragma unroll
;             for (int jp = 0; jp < 2; ++jp) {
;                 float o[4];
; #pragma unroll
;                 for (int r = 0; r < 4; ++r) { const float g = acc[i][2 * jp][r], u = acc[i][2 * jp + 1][r]; o[r] = g / (1.f + __expf(-g)) * u; }
;                 u32x2 w; w[0] = pk2(o[0], o[1]); w[1] = pk2(o[2], o[3]);
;                 *(u32x2*)(actb + tiled_off(rowb + i * 16, colb + jp * 16, FFH)) = w;
;             }
	v_div_fmas_f32 v53, v53, v54, v56
	v_div_fixup_f32 v47, v53, v51, v47
	v_div_scale_f32 v51, s[0:1], v50, v50, v46
	v_rcp_f32_e32 v53, v51
	s_nop 0
	v_fma_f32 v54, -v51, v53, 1.0
	v_fmac_f32_e32 v53, v54, v53
	v_div_scale_f32 v54, vcc, v46, v50, v46
	v_mul_f32_e32 v55, v54, v53
	v_fma_f32 v56, -v51, v55, v54
	v_fmac_f32_e32 v55, v56, v53
	v_fma_f32 v51, -v51, v55, v54
	v_div_fmas_f32 v51, v51, v53, v55
	v_div_fixup_f32 v46, v51, v50, v46
	v_pk_mul_f32 v[42:43], v[42:43], v[46:47]
	v_mul_f32_e32 v46, 0xbfb8aa3b, v48
	v_mul_f32_e32 v47, 0xbfb8aa3b, v49
	v_exp_f32_e32 v46, v46
	v_exp_f32_e32 v47, v47
	v_cvt_pk_bf16_f32 v42, v42, v43
	v_pk_add_f32 v[46:47], v[46:47], 1.0 op_sel_hi:[1,0]
	s_nop 0
	v_div_scale_f32 v50, s[0:1], v47, v47, v49
	v_rcp_f32_e32 v51, v50
	s_nop 0
	v_fma_f32 v53, -v50, v51, 1.0
	v_fmac_f32_e32 v51, v53, v51
	v_div_scale_f32 v53, vcc, v49, v47, v49
	v_mul_f32_e32 v54, v53, v51
	v_fma_f32 v55, -v50, v54, v53
	v_fmac_f32_e32 v54, v55, v51
	v_fma_f32 v50, -v50, v54, v53
	v_div_fmas_f32 v50, v50, v51, v54
	v_div_fixup_f32 v47, v50, v47, v49
	v_div_scale_f32 v49, s[0:1], v46, v46, v48
	v_rcp_f32_e32 v50, v49
	s_nop 0
	v_fma_f32 v51, -v49, v50, 1.0
	v_fmac_f32_e32 v50, v51, v50
	v_div_scale_f32 v51, vcc, v48, v46, v48
	v_mul_f32_e32 v53, v51, v50
	v_fma_f32 v54, -v49, v53, v51
	v_fmac_f32_e32 v53, v54, v50
	v_fma_f32 v49, -v49, v53, v51
	v_div_fmas_f32 v49, v49, v50, v53
	v_div_fixup_f32 v46, v49, v46, v48
	v_pk_mul_f32 v[44:45], v[44:45], v[46:47]
	s_nop 0
	v_cvt_pk_bf16_f32 v43, v44, v45
	v_mad_i64_i32 v[44:45], s[0:1], v52, s16, v[90:91]
	v_lshlrev_b64 v[44:45], 10, v[44:45]
	v_lshl_add_u64 v[44:45], v[98:99], 0, v[44:45]
	v_lshl_add_u64 v[44:45], v[44:45], 0, v[0:1]
	v_mov_b32_e32 v252, v42
	v_mov_b32_e32 v253, v43
	v_mul_f32_e32 v42, 0xbfb8aa3b, v34
	v_mul_f32_e32 v43, 0xbfb8aa3b, v35
	v_exp_f32_e32 v42, v42
	v_exp_f32_e32 v43, v43
	s_nop 0
	v_pk_add_f32 v[42:43], v[42:43], 1.0 op_sel_hi:[1,0]
	s_nop 0
	v_div_scale_f32 v46, s[0:1], v43, v43, v35
	v_rcp_f32_e32 v47, v46
	s_nop 0
	v_fma_f32 v48, -v46, v47, 1.0
	v_fmac_f32_e32 v47, v48, v47
	v_div_scale_f32 v48, vcc, v35, v43, v35
	v_mul_f32_e32 v49, v48, v47
	v_fma_f32 v50, -v46, v49, v48
	v_fmac_f32_e32 v49, v50, v47
	v_fma_f32 v46, -v46, v49, v48
	v_div_fmas_f32 v46, v46, v47, v49
	v_div_fixup_f32 v35, v46, v43, v35
	v_div_scale_f32 v43, s[0:1], v42, v42, v34
	v_rcp_f32_e32 v46, v43
	s_nop 0
	v_fma_f32 v47, -v43, v46, 1.0
	v_fmac_f32_e32 v46, v47, v46
	v_div_scale_f32 v47, vcc, v34, v42, v34
	v_mul_f32_e32 v48, v47, v46
	v_fma_f32 v49, -v43, v48, v47
	v_fmac_f32_e32 v48, v49, v46
	v_fma_f32 v43, -v43, v48, v47
	v_div_fmas_f32 v43, v43, v46, v48
	v_div_fixup_f32 v34, v43, v42, v34
	v_pk_mul_f32 v[34:35], v[38:39], v[34:35]
	v_mul_f32_e32 v38, 0xbfb8aa3b, v36
	v_mul_f32_e32 v39, 0xbfb8aa3b, v37
	v_exp_f32_e32 v38, v38
	v_exp_f32_e32 v39, v39
	v_cvt_pk_bf16_f32 v34, v34, v35
	v_pk_add_f32 v[38:39], v[38:39], 1.0 op_sel_hi:[1,0]
	s_nop 0
	v_div_scale_f32 v42, s[0:1], v39, v39, v37
	v_rcp_f32_e32 v43, v42
	s_nop 0
	v_fma_f32 v46, -v42, v43, 1.0
	v_fmac_f32_e32 v43, v46, v43
	v_div_scale_f32 v46, vcc, v37, v39, v37
	v_mul_f32_e32 v47, v46, v43
	v_fma_f32 v48, -v42, v47, v46
	v_fmac_f32_e32 v47, v48, v43
	v_fma_f32 v42, -v42, v47, v46
	v_div_fmas_f32 v42, v42, v43, v47
	v_div_fixup_f32 v37, v42, v39, v37
	v_div_scale_f32 v39, s[0:1], v38, v38, v36
	v_rcp_f32_e32 v42, v39
	s_nop 0
	v_fma_f32 v43, -v39, v42, 1.0
	v_fmac_f32_e32 v42, v43, v42
	v_div_scale_f32 v43, vcc, v36, v38, v36
	v_mul_f32_e32 v46, v43, v42
	v_fma_f32 v47, -v39, v46, v43
	v_fmac_f32_e32 v46, v47, v42
	v_fma_f32 v39, -v39, v46, v43
	v_div_fmas_f32 v39, v39, v42, v46
	v_div_fixup_f32 v36, v39, v38, v36
	v_pk_mul_f32 v[36:37], v[40:41], v[36:37]
	s_nop 0
	v_cvt_pk_bf16_f32 v35, v36, v37
	v_mov_b32_e32 v254, v34
	v_mov_b32_e32 v255, v35
	s_nop 1
	v_permlane16_swap_b32_e32 v252, v254
	v_permlane16_swap_b32_e32 v253, v255
	global_store_dwordx4 v[44:45], v[252:255], off
	v_add_u32_e32 v34, 64, v100
	v_ashrrev_i32_e32 v36, 4, v34
	v_mul_f32_e32 v34, 0xbfb8aa3b, v30
	v_mul_f32_e32 v35, 0xbfb8aa3b, v31
	v_exp_f32_e32 v34, v34
	v_exp_f32_e32 v35, v35
	s_nop 0
	v_pk_add_f32 v[34:35], v[34:35], 1.0 op_sel_hi:[1,0]
	s_nop 0
	v_div_scale_f32 v37, s[0:1], v35, v35, v31
	v_rcp_f32_e32 v38, v37
	s_nop 0
	v_fma_f32 v39, -v37, v38, 1.0
	v_fmac_f32_e32 v38, v39, v38
	v_div_scale_f32 v39, vcc, v31, v35, v31
	v_mul_f32_e32 v40, v39, v38
	v_fma_f32 v41, -v37, v40, v39
	v_fmac_f32_e32 v40, v41, v38
	v_fma_f32 v37, -v37, v40, v39
	v_div_fmas_f32 v37, v37, v38, v40
	v_div_fixup_f32 v31, v37, v35, v31
	v_div_scale_f32 v35, s[0:1], v34, v34, v30
	v_rcp_f32_e32 v37, v35
	s_nop 0
	v_fma_f32 v38, -v35, v37, 1.0
	v_fmac_f32_e32 v37, v38, v37
	v_div_scale_f32 v38, vcc, v30, v34, v30
	v_mul_f32_e32 v39, v38, v37
	v_fma_f32 v40, -v35, v39, v38
	v_fmac_f32_e32 v39, v40, v37
	v_fma_f32 v35, -v35, v39, v38
	v_div_fmas_f32 v35, v35, v37, v39
	v_div_fixup_f32 v30, v35, v34, v30
	v_pk_mul_f32 v[26:27], v[26:27], v[30:31]
	v_mul_f32_e32 v30, 0xbfb8aa3b, v32
	v_mul_f32_e32 v31, 0xbfb8aa3b, v33
	v_exp_f32_e32 v30, v30
	v_exp_f32_e32 v31, v31
	v_cvt_pk_bf16_f32 v26, v26, v27
	v_pk_add_f32 v[30:31], v[30:31], 1.0 op_sel_hi:[1,0]
	s_nop 0
	v_div_scale_f32 v34, s[0:1], v31, v31, v33
	v_rcp_f32_e32 v35, v34
	s_nop 0
	v_fma_f32 v37, -v34, v35, 1.0
	v_fmac_f32_e32 v35, v37, v35
	v_div_scale_f32 v37, vcc, v33, v31, v33
	v_mul_f32_e32 v38, v37, v35
	v_fma_f32 v39, -v34, v38, v37
	v_fmac_f32_e32 v38, v39, v35
	v_fma_f32 v34, -v34, v38, v37
	v_div_fmas_f32 v34, v34, v35, v38
	v_div_fixup_f32 v31, v34, v31, v33
	v_div_scale_f32 v33, s[0:1], v30, v30, v32
; __device__ __forceinline__ size_t tiled_off(int row, int k, int K) { return ((size_t)(row >> 4) * (K >> 5) + (k >> 5)) * 512 + (row & 15) * 32 + (k & 31); }
; template <int EPI>
; __device__ __forceinline__ void gemm_tile3(const Params& p, int l, const u16* __restrict__ A, int lda, const u16* __restrict__ Bt, int K, int m0, int n0, unsigned char* smem) {
;     ...
;         u16* actb = (u16*)(p.ws + OFF_ACT);
;         const int colb = (n0 >> 1) + wc * 32 + fq * 4;
; #pragma unroll
;         for (int i = 0; i < 6; ++i)
; #pragma unroll
;             for (int jp = 0; jp < 2; ++jp) {
;                 float o[4];
; #pragma unroll
;                 for (int r = 0; r < 4; ++r) { const float g = acc[i][2 * jp][r], u = acc[i][2 * jp + 1][r]; o[r] = g / (1.f + __expf(-g)) * u; }
;                 u32x2 w; w[0] = pk2(o[0], o[1]); w[1] = pk2(o[2], o[3]);
;                 *(u32x2*)(actb + tiled_off(rowb + i * 16, colb + jp * 16, FFH)) = w;
;             }
	v_rcp_f32_e32 v34, v33
	s_nop 0
	v_fma_f32 v35, -v33, v34, 1.0
	v_fmac_f32_e32 v34, v35, v34
	v_div_scale_f32 v35, vcc, v32, v30, v32
	v_mul_f32_e32 v37, v35, v34
	v_fma_f32 v38, -v33, v37, v35
	v_fmac_f32_e32 v37, v38, v34
	v_fma_f32 v33, -v33, v37, v35
	v_div_fmas_f32 v33, v33, v34, v37
	v_div_fixup_f32 v30, v33, v30, v32
	v_pk_mul_f32 v[28:29], v[28:29], v[30:31]
	s_nop 0
	v_cvt_pk_bf16_f32 v27, v28, v29
	v_mad_i64_i32 v[28:29], s[0:1], v36, s16, v[90:91]
	v_lshlrev_b64 v[28:29], 10, v[28:29]
	v_lshl_add_u64 v[28:29], v[98:99], 0, v[28:29]
	v_lshl_add_u64 v[28:29], v[28:29], 0, v[0:1]
	v_mov_b32_e32 v252, v26
	v_mov_b32_e32 v253, v27
	v_mul_f32_e32 v26, 0xbfb8aa3b, v18
	v_mul_f32_e32 v27, 0xbfb8aa3b, v19
	v_exp_f32_e32 v26, v26
	v_exp_f32_e32 v27, v27
	s_nop 0
	v_pk_add_f32 v[26:27], v[26:27], 1.0 op_sel_hi:[1,0]
	s_nop 0
	v_div_scale_f32 v30, s[0:1], v27, v27, v19
	v_rcp_f32_e32 v31, v30
	s_nop 0
	v_fma_f32 v32, -v30, v31, 1.0
	v_fmac_f32_e32 v31, v32, v31
	v_div_scale_f32 v32, vcc, v19, v27, v19
	v_mul_f32_e32 v33, v32, v31
	v_fma_f32 v34, -v30, v33, v32
	v_fmac_f32_e32 v33, v34, v31
	v_fma_f32 v30, -v30, v33, v32
	v_div_fmas_f32 v30, v30, v31, v33
	v_div_fixup_f32 v19, v30, v27, v19
	v_div_scale_f32 v27, s[0:1], v26, v26, v18
	v_rcp_f32_e32 v30, v27
	s_nop 0
	v_fma_f32 v31, -v27, v30, 1.0
	v_fmac_f32_e32 v30, v31, v30
	v_div_scale_f32 v31, vcc, v18, v26, v18
	v_mul_f32_e32 v32, v31, v30
	v_fma_f32 v33, -v27, v32, v31
	v_fmac_f32_e32 v32, v33, v30
	v_fma_f32 v27, -v27, v32, v31
	v_div_fmas_f32 v27, v27, v30, v32
	v_div_fixup_f32 v18, v27, v26, v18
	v_pk_mul_f32 v[18:19], v[22:23], v[18:19]
	v_mul_f32_e32 v22, 0xbfb8aa3b, v20
	v_mul_f32_e32 v23, 0xbfb8aa3b, v21
	v_exp_f32_e32 v22, v22
	v_exp_f32_e32 v23, v23
	v_cvt_pk_bf16_f32 v18, v18, v19
	v_pk_add_f32 v[22:23], v[22:23], 1.0 op_sel_hi:[1,0]
	s_nop 0
	v_div_scale_f32 v26, s[0:1], v23, v23, v21
	v_rcp_f32_e32 v27, v26
	s_nop 0
	v_fma_f32 v30, -v26, v27, 1.0
	v_fmac_f32_e32 v27, v30, v27
	v_div_scale_f32 v30, vcc, v21, v23, v21
	v_mul_f32_e32 v31, v30, v27
	v_fma_f32 v32, -v26, v31, v30
	v_fmac_f32_e32 v31, v32, v27
	v_fma_f32 v26, -v26, v31, v30
	v_div_fmas_f32 v26, v26, v27, v31
	v_div_fixup_f32 v21, v26, v23, v21
	v_div_scale_f32 v23, s[0:1], v22, v22, v20
	v_rcp_f32_e32 v26, v23
	s_nop 0
	v_fma_f32 v27, -v23, v26, 1.0
	v_fmac_f32_e32 v26, v27, v26
	v_div_scale_f32 v27, vcc, v20, v22, v20
	v_mul_f32_e32 v30, v27, v26
	v_fma_f32 v31, -v23, v30, v27
	v_fmac_f32_e32 v30, v31, v26
	v_fma_f32 v23, -v23, v30, v27
	v_div_fmas_f32 v23, v23, v26, v30
	v_div_fixup_f32 v20, v23, v22, v20
	v_pk_mul_f32 v[20:21], v[24:25], v[20:21]
	s_nop 0
	v_cvt_pk_bf16_f32 v19, v20, v21
	v_mov_b32_e32 v254, v18
	v_mov_b32_e32 v255, v19
	s_nop 1
	v_permlane16_swap_b32_e32 v252, v254
	v_permlane16_swap_b32_e32 v253, v255
	global_store_dwordx4 v[28:29], v[252:255], off
	v_add_u32_e32 v18, 0x50, v100
	v_ashrrev_i32_e32 v20, 4, v18
	v_mul_f32_e32 v18, 0xbfb8aa3b, v14
	v_mul_f32_e32 v19, 0xbfb8aa3b, v15
	v_exp_f32_e32 v18, v18
	v_exp_f32_e32 v19, v19
	s_nop 0
	v_pk_add_f32 v[18:19], v[18:19], 1.0 op_sel_hi:[1,0]
	s_nop 0
	v_div_scale_f32 v21, s[0:1], v19, v19, v15
	v_rcp_f32_e32 v22, v21
	s_nop 0
	v_fma_f32 v23, -v21, v22, 1.0
	v_fmac_f32_e32 v22, v23, v22
	v_div_scale_f32 v23, vcc, v15, v19, v15
	v_mul_f32_e32 v24, v23, v22
	v_fma_f32 v25, -v21, v24, v23
	v_fmac_f32_e32 v24, v25, v22
	v_fma_f32 v21, -v21, v24, v23
	v_div_fmas_f32 v21, v21, v22, v24
	v_div_fixup_f32 v15, v21, v19, v15
	v_div_scale_f32 v19, s[0:1], v18, v18, v14
	v_rcp_f32_e32 v21, v19
	s_nop 0
	v_fma_f32 v22, -v19, v21, 1.0
	v_fmac_f32_e32 v21, v22, v21
	v_div_scale_f32 v22, vcc, v14, v18, v14
	v_mul_f32_e32 v23, v22, v21
; __device__ __forceinline__ size_t tiled_off(int row, int k, int K) { return ((size_t)(row >> 4) * (K >> 5) + (k >> 5)) * 512 + (row & 15) * 32 + (k & 31); }
; template <int EPI>
; __device__ __forceinline__ void gemm_tile3(const Params& p, int l, const u16* __restrict__ A, int lda, const u16* __restrict__ Bt, int K, int m0, int n0, unsigned char* smem) {
;     ...
;         u16* actb = (u16*)(p.ws + OFF_ACT);
;         const int colb = (n0 >> 1) + wc * 32 + fq * 4;
; #pragma unroll
;         for (int i = 0; i < 6; ++i)
; #pragma unroll
;             for (int jp = 0; jp < 2; ++jp) {
;                 float o[4];
; #pragma unroll
;                 for (int r = 0; r < 4; ++r) { const float g = acc[i][2 * jp][r], u = acc[i][2 * jp + 1][r]; o[r] = g / (1.f + __expf(-g)) * u; }
;                 u32x2 w; w[0] = pk2(o[0], o[1]); w[1] = pk2(o[2], o[3]);
;                 *(u32x2*)(actb + tiled_off(rowb + i * 16, colb + jp * 16, FFH)) = w;
;             }
; __device__ __forceinline__ bool tile_order(int r, int total, int nN, int& mt, int& nt) {
;     const int nloc = gridDim.x >> 3, xcd = blockIdx.x & 7, li = blockIdx.x >> 3;
;     const int L = (r * 8 + xcd) * nloc + li;
;     if (L >= total) return false;
	v_fma_f32 v24, -v19, v23, v22
	v_fmac_f32_e32 v23, v24, v21
	v_fma_f32 v19, -v19, v23, v22
	v_div_fmas_f32 v19, v19, v21, v23
	v_div_fixup_f32 v14, v19, v18, v14
	v_pk_mul_f32 v[10:11], v[10:11], v[14:15]
	v_mul_f32_e32 v14, 0xbfb8aa3b, v16
	v_mul_f32_e32 v15, 0xbfb8aa3b, v17
	v_exp_f32_e32 v14, v14
	v_exp_f32_e32 v15, v15
	v_cvt_pk_bf16_f32 v10, v10, v11
	v_pk_add_f32 v[14:15], v[14:15], 1.0 op_sel_hi:[1,0]
	s_nop 0
	v_div_scale_f32 v18, s[0:1], v15, v15, v17
	v_rcp_f32_e32 v19, v18
	s_nop 0
	v_fma_f32 v21, -v18, v19, 1.0
	v_fmac_f32_e32 v19, v21, v19
	v_div_scale_f32 v21, vcc, v17, v15, v17
	v_mul_f32_e32 v22, v21, v19
	v_fma_f32 v23, -v18, v22, v21
	v_fmac_f32_e32 v22, v23, v19
	v_fma_f32 v18, -v18, v22, v21
	v_div_fmas_f32 v18, v18, v19, v22
	v_div_fixup_f32 v15, v18, v15, v17
	v_div_scale_f32 v17, s[0:1], v14, v14, v16
	v_rcp_f32_e32 v18, v17
	s_nop 0
	v_fma_f32 v19, -v17, v18, 1.0
	v_fmac_f32_e32 v18, v19, v18
	v_div_scale_f32 v19, vcc, v16, v14, v16
	v_mul_f32_e32 v21, v19, v18
	v_fma_f32 v22, -v17, v21, v19
	v_fmac_f32_e32 v21, v22, v18
	v_fma_f32 v17, -v17, v21, v19
	v_div_fmas_f32 v17, v17, v18, v21
	v_div_fixup_f32 v14, v17, v14, v16
	v_pk_mul_f32 v[12:13], v[12:13], v[14:15]
	s_nop 0
	v_cvt_pk_bf16_f32 v11, v12, v13
	v_mad_i64_i32 v[12:13], s[0:1], v20, s16, v[90:91]
	v_lshlrev_b64 v[12:13], 10, v[12:13]
	v_lshl_add_u64 v[12:13], v[98:99], 0, v[12:13]
	v_lshl_add_u64 v[12:13], v[12:13], 0, v[0:1]
	v_mul_f32_e32 v0, 0xbfb8aa3b, v6
	v_mov_b32_e32 v252, v10
	v_mov_b32_e32 v253, v11
	v_exp_f32_e32 v10, v0
	v_mul_f32_e32 v0, 0xbfb8aa3b, v7
	v_exp_f32_e32 v11, v0
	s_nop 0
	v_pk_add_f32 v[10:11], v[10:11], 1.0 op_sel_hi:[1,0]
	s_nop 0
	v_div_scale_f32 v0, s[0:1], v11, v11, v7
	v_rcp_f32_e32 v14, v0
	s_nop 0
	v_fma_f32 v15, -v0, v14, 1.0
	v_fmac_f32_e32 v14, v15, v14
	v_div_scale_f32 v15, vcc, v7, v11, v7
	v_mul_f32_e32 v16, v15, v14
	v_fma_f32 v17, -v0, v16, v15
	v_fmac_f32_e32 v16, v17, v14
	v_fma_f32 v0, -v0, v16, v15
	v_div_fmas_f32 v0, v0, v14, v16
	v_div_fixup_f32 v7, v0, v11, v7
	v_div_scale_f32 v0, s[0:1], v10, v10, v6
	v_rcp_f32_e32 v11, v0
	s_nop 0
	v_fma_f32 v14, -v0, v11, 1.0
	v_fmac_f32_e32 v11, v14, v11
	v_div_scale_f32 v14, vcc, v6, v10, v6
	v_mul_f32_e32 v15, v14, v11
	v_fma_f32 v16, -v0, v15, v14
	v_fmac_f32_e32 v15, v16, v11
	v_fma_f32 v0, -v0, v15, v14
	v_div_fmas_f32 v0, v0, v11, v15
	v_div_fixup_f32 v6, v0, v10, v6
	v_mul_f32_e32 v0, 0xbfb8aa3b, v8
	v_pk_mul_f32 v[2:3], v[2:3], v[6:7]
	v_exp_f32_e32 v6, v0
	v_mul_f32_e32 v0, 0xbfb8aa3b, v9
	v_exp_f32_e32 v7, v0
	v_cvt_pk_bf16_f32 v2, v2, v3
	v_pk_add_f32 v[6:7], v[6:7], 1.0 op_sel_hi:[1,0]
	s_nop 0
	v_div_scale_f32 v0, s[0:1], v7, v7, v9
	v_rcp_f32_e32 v10, v0
	s_nop 0
	v_fma_f32 v11, -v0, v10, 1.0
	v_fmac_f32_e32 v10, v11, v10
	v_div_scale_f32 v11, vcc, v9, v7, v9
	v_mul_f32_e32 v14, v11, v10
	v_fma_f32 v15, -v0, v14, v11
	v_fmac_f32_e32 v14, v15, v10
	v_fma_f32 v0, -v0, v14, v11
	v_div_fmas_f32 v0, v0, v10, v14
	v_div_fixup_f32 v7, v0, v7, v9
	v_div_scale_f32 v0, s[0:1], v6, v6, v8
	v_rcp_f32_e32 v9, v0
	s_lshl_b32 s0, s41, 3
	s_or_b32 s0, s0, s53
	s_mul_i32 s0, s0, s52
	v_fma_f32 v10, -v0, v9, 1.0
	v_fmac_f32_e32 v9, v10, v9
	v_div_scale_f32 v10, vcc, v8, v6, v8
	v_mul_f32_e32 v11, v10, v9
	v_fma_f32 v14, -v0, v11, v10
	v_fmac_f32_e32 v11, v14, v9
	v_fma_f32 v0, -v0, v11, v10
	v_div_fmas_f32 v0, v0, v9, v11
	v_div_fixup_f32 v6, v0, v6, v8
	v_pk_mul_f32 v[4:5], v[4:5], v[6:7]
	s_add_i32 s0, s0, s33
	v_cvt_pk_bf16_f32 v3, v4, v5
	s_cmp_lt_u32 s0, s38
	v_mov_b32_e32 v254, v2
	v_mov_b32_e32 v255, v3
	s_nop 1
	v_permlane16_swap_b32_e32 v252, v254
	v_permlane16_swap_b32_e32 v253, v255
	global_store_dwordx4 v[12:13], v[252:255], off
	s_cbranch_scc0 .LBB0_905
